# GEMM1 epilogue basic-block layout: per-row-group blocks regrouped by tile kind so a unit walks adjacent code (cold far jumps cost ~170 ns each); no instruction changed
# baseline (speedup 1.0000x reference)
; __device__ __forceinline__ float gelu_tanh(float x) { const float u = 1.5957691216f * (x + 0.044715f * x * x * x); return x * __builtin_amdgcn_rcpf(1.f + __expf(-u)); }
; __device__ __forceinline__ void st_bf16x8(bf16_t* p, const f32x4 a, const f32x4 b) { uint4 o; o.x = cvt_pk_bf16(a[0], a[1]); o.y = cvt_pk_bf16(a[2], a[3]); o.z = cvt_pk_bf16(b[0], b[1]); o.w = cvt_pk_bf16(b[2], b[3]); *(uint4*)p = o; }
;     __device__ __forceinline__ void row(const f32x4 (&a)[2][2], int row, int pn, int wc, int fq) const {
;         if (pn < 2 || pn == 4 || pn == 5) {
;             bf16_t* dst = (pn < 2 ? pU : pBG) + (size_t)row * 512 + (pn & 1) * 256 + wc * 32 + 8 * fq;
; #pragma unroll
;             for (int bj = 0; bj < 2; ++bj) { f32x4 v0 = a[bj][0], v1 = a[bj][1];
;                 if (pn < 2) {
; #pragma unroll
;                     for (int j = 0; j < 4; ++j) { v0[j] = gelu_tanh(v0[j]); v1[j] = gelu_tanh(v1[j]); } }
;                 st_bf16x8(dst + bj * HALF, v0, v1); }
.LBB0_235:
	s_andn2_b64 vcc, exec, s[0:1]
	s_cbranch_vccz .LBB0_278
	s_branch .LBB0_283
.LBB0_246:
	s_and_b64 vcc, exec, s[4:5]
	s_cbranch_vccnz .LBB0_248
	v_mov_b32_e32 v190, 0x3d372713
	v_mov_b32_e32 v192, 0xbfcc422a
	v_mov_b32_e32 v194, 0x3fb8aa3b
	v_pk_mul_f32 v[196:197], v[104:105], v[190:191] op_sel_hi:[1,0]
	v_pk_mul_f32 v[198:199], v[106:107], v[190:191] op_sel_hi:[1,0]
	v_pk_mul_f32 v[200:201], v[108:109], v[190:191] op_sel_hi:[1,0]
	v_pk_mul_f32 v[202:203], v[110:111], v[190:191] op_sel_hi:[1,0]
	v_pk_mul_f32 v[196:197], v[104:105], v[196:197]
	v_pk_mul_f32 v[198:199], v[106:107], v[198:199]
	v_pk_mul_f32 v[200:201], v[108:109], v[200:201]
	v_pk_mul_f32 v[202:203], v[110:111], v[202:203]
	v_pk_fma_f32 v[196:197], v[104:105], v[196:197], v[104:105]
	v_pk_fma_f32 v[198:199], v[106:107], v[198:199], v[106:107]
	v_pk_fma_f32 v[200:201], v[108:109], v[200:201], v[108:109]
	v_pk_fma_f32 v[202:203], v[110:111], v[202:203], v[110:111]
	v_pk_mul_f32 v[196:197], v[196:197], v[192:193] op_sel_hi:[1,0]
	v_pk_mul_f32 v[198:199], v[198:199], v[192:193] op_sel_hi:[1,0]
	v_pk_mul_f32 v[200:201], v[200:201], v[192:193] op_sel_hi:[1,0]
	v_pk_mul_f32 v[202:203], v[202:203], v[192:193] op_sel_hi:[1,0]
	v_pk_mul_f32 v[196:197], v[196:197], v[194:195] op_sel_hi:[1,0]
	v_pk_mul_f32 v[198:199], v[198:199], v[194:195] op_sel_hi:[1,0]
	v_pk_mul_f32 v[200:201], v[200:201], v[194:195] op_sel_hi:[1,0]
	v_pk_mul_f32 v[202:203], v[202:203], v[194:195] op_sel_hi:[1,0]
	v_exp_f32_e32 v196, v196
	v_exp_f32_e32 v197, v197
	v_exp_f32_e32 v198, v198
	v_exp_f32_e32 v199, v199
	v_exp_f32_e32 v200, v200
	v_exp_f32_e32 v201, v201
	v_exp_f32_e32 v202, v202
	v_exp_f32_e32 v203, v203
	v_pk_add_f32 v[196:197], v[196:197], 1.0 op_sel_hi:[1,0]
	v_pk_add_f32 v[198:199], v[198:199], 1.0 op_sel_hi:[1,0]
	v_pk_add_f32 v[200:201], v[200:201], 1.0 op_sel_hi:[1,0]
	v_pk_add_f32 v[202:203], v[202:203], 1.0 op_sel_hi:[1,0]
	v_rcp_f32_e32 v196, v196
	v_rcp_f32_e32 v197, v197
	v_rcp_f32_e32 v198, v198
	v_rcp_f32_e32 v199, v199
	v_rcp_f32_e32 v200, v200
	v_rcp_f32_e32 v201, v201
	v_rcp_f32_e32 v202, v202
	v_rcp_f32_e32 v203, v203
	v_pk_mul_f32 v[104:105], v[104:105], v[196:197]
	v_pk_mul_f32 v[106:107], v[106:107], v[198:199]
	v_pk_mul_f32 v[108:109], v[108:109], v[200:201]
	v_pk_mul_f32 v[110:111], v[110:111], v[202:203]
	s_nop 0
	s_nop 0
	s_nop 0
	s_nop 0

; __device__ __forceinline__ float gelu_tanh(float x) { const float u = 1.5957691216f * (x + 0.044715f * x * x * x); return x * __builtin_amdgcn_rcpf(1.f + __expf(-u)); }
; __device__ __forceinline__ void st_bf16x8(bf16_t* p, const f32x4 a, const f32x4 b) { uint4 o; o.x = cvt_pk_bf16(a[0], a[1]); o.y = cvt_pk_bf16(a[2], a[3]); o.z = cvt_pk_bf16(b[0], b[1]); o.w = cvt_pk_bf16(b[2], b[3]); *(uint4*)p = o; }
;     __device__ __forceinline__ void row(const f32x4 (&a)[2][2], int row, int pn, int wc, int fq) const {
;     ...
;             for (int bj = 0; bj < 2; ++bj) { f32x4 v0 = a[bj][0], v1 = a[bj][1];
;                 if (pn < 2) {
; #pragma unroll
;                     for (int j = 0; j < 4; ++j) { v0[j] = gelu_tanh(v0[j]); v1[j] = gelu_tanh(v1[j]); } }
;                 st_bf16x8(dst + bj * HALF, v0, v1); }
.LBB0_250:
	v_cvt_pk_bf16_f32 v100, v100, v101
	v_cvt_pk_bf16_f32 v101, v102, v103
	v_cvt_pk_bf16_f32 v102, v96, v97
	s_nop 0
	v_cvt_pk_bf16_f32 v103, v98, v99
	global_store_dwordx4 v[112:113], v[100:103], off offset:256
	v_or_b32_e32 v104, 32, v156
	s_and_b64 vcc, exec, s[8:9]
	s_mov_b64 s[0:1], -1
	s_cbranch_vccnz .LBB0_233
	s_branch .LBB0_251

; __device__ __forceinline__ float gelu_tanh(float x) { const float u = 1.5957691216f * (x + 0.044715f * x * x * x); return x * __builtin_amdgcn_rcpf(1.f + __expf(-u)); }
; __device__ __forceinline__ void st_bf16x8(bf16_t* p, const f32x4 a, const f32x4 b) { uint4 o; o.x = cvt_pk_bf16(a[0], a[1]); o.y = cvt_pk_bf16(a[2], a[3]); o.z = cvt_pk_bf16(b[0], b[1]); o.w = cvt_pk_bf16(b[2], b[3]); *(uint4*)p = o; }
;     __device__ __forceinline__ void row(const f32x4 (&a)[2][2], int row, int pn, int wc, int fq) const {
;     ...
;             for (int bj = 0; bj < 2; ++bj) { f32x4 v0 = a[bj][0], v1 = a[bj][1];
;                 if (pn < 2) {
; #pragma unroll
;                     for (int j = 0; j < 4; ++j) { v0[j] = gelu_tanh(v0[j]); v1[j] = gelu_tanh(v1[j]); } }
;                 st_bf16x8(dst + bj * HALF, v0, v1); }
.LBB0_265:
	v_cvt_pk_bf16_f32 v84, v84, v85
	v_cvt_pk_bf16_f32 v85, v86, v87
	v_cvt_pk_bf16_f32 v86, v80, v81
	s_nop 0
	v_cvt_pk_bf16_f32 v87, v82, v83
	global_store_dwordx4 v[96:97], v[84:87], off offset:256
	v_or_b32_e32 v88, 48, v156
	s_and_b64 vcc, exec, s[8:9]
	s_mov_b64 s[0:1], -1
	s_cbranch_vccnz .LBB0_235
	s_branch .LBB0_266

; __device__ __forceinline__ float gelu_tanh(float x) { const float u = 1.5957691216f * (x + 0.044715f * x * x * x); return x * __builtin_amdgcn_rcpf(1.f + __expf(-u)); }
; __device__ __forceinline__ void st_bf16x8(bf16_t* p, const f32x4 a, const f32x4 b) { uint4 o; o.x = cvt_pk_bf16(a[0], a[1]); o.y = cvt_pk_bf16(a[2], a[3]); o.z = cvt_pk_bf16(b[0], b[1]); o.w = cvt_pk_bf16(b[2], b[3]); *(uint4*)p = o; }
;     __device__ __forceinline__ void row(const f32x4 (&a)[2][2], int row, int pn, int wc, int fq) const {
;     ...
;             for (int bj = 0; bj < 2; ++bj) { f32x4 v0 = a[bj][0], v1 = a[bj][1];
;                 if (pn < 2) {
; #pragma unroll
;                     for (int j = 0; j < 4; ++j) { v0[j] = gelu_tanh(v0[j]); v1[j] = gelu_tanh(v1[j]); } }
;                 st_bf16x8(dst + bj * HALF, v0, v1); }
.LBB0_290:
	s_andn2_b64 vcc, exec, s[0:1]
	s_cbranch_vccnz .LBB0_208
	s_branch .LBB0_352
.LBB0_302:
	s_and_b64 vcc, exec, s[4:5]
	s_cbranch_vccnz .LBB0_304
	v_mov_b32_e32 v190, 0x3d372713
	v_mov_b32_e32 v192, 0xbfcc422a
	v_mov_b32_e32 v194, 0x3fb8aa3b
	v_pk_mul_f32 v[196:197], v[56:57], v[190:191] op_sel_hi:[1,0]
	v_pk_mul_f32 v[198:199], v[58:59], v[190:191] op_sel_hi:[1,0]
	v_pk_mul_f32 v[200:201], v[60:61], v[190:191] op_sel_hi:[1,0]
	v_pk_mul_f32 v[202:203], v[62:63], v[190:191] op_sel_hi:[1,0]
	v_pk_mul_f32 v[196:197], v[56:57], v[196:197]
	v_pk_mul_f32 v[198:199], v[58:59], v[198:199]
	v_pk_mul_f32 v[200:201], v[60:61], v[200:201]
	v_pk_mul_f32 v[202:203], v[62:63], v[202:203]
	v_pk_fma_f32 v[196:197], v[56:57], v[196:197], v[56:57]
	v_pk_fma_f32 v[198:199], v[58:59], v[198:199], v[58:59]
	v_pk_fma_f32 v[200:201], v[60:61], v[200:201], v[60:61]
	v_pk_fma_f32 v[202:203], v[62:63], v[202:203], v[62:63]
	v_pk_mul_f32 v[196:197], v[196:197], v[192:193] op_sel_hi:[1,0]
	v_pk_mul_f32 v[198:199], v[198:199], v[192:193] op_sel_hi:[1,0]
	v_pk_mul_f32 v[200:201], v[200:201], v[192:193] op_sel_hi:[1,0]
	v_pk_mul_f32 v[202:203], v[202:203], v[192:193] op_sel_hi:[1,0]
	v_pk_mul_f32 v[196:197], v[196:197], v[194:195] op_sel_hi:[1,0]
	v_pk_mul_f32 v[198:199], v[198:199], v[194:195] op_sel_hi:[1,0]
	v_pk_mul_f32 v[200:201], v[200:201], v[194:195] op_sel_hi:[1,0]
	v_pk_mul_f32 v[202:203], v[202:203], v[194:195] op_sel_hi:[1,0]
	v_exp_f32_e32 v196, v196
	v_exp_f32_e32 v197, v197
	v_exp_f32_e32 v198, v198
	v_exp_f32_e32 v199, v199
	v_exp_f32_e32 v200, v200
	v_exp_f32_e32 v201, v201
	v_exp_f32_e32 v202, v202
	v_exp_f32_e32 v203, v203
	v_pk_add_f32 v[196:197], v[196:197], 1.0 op_sel_hi:[1,0]
	v_pk_add_f32 v[198:199], v[198:199], 1.0 op_sel_hi:[1,0]
	v_pk_add_f32 v[200:201], v[200:201], 1.0 op_sel_hi:[1,0]
	v_pk_add_f32 v[202:203], v[202:203], 1.0 op_sel_hi:[1,0]
	v_rcp_f32_e32 v196, v196
	v_rcp_f32_e32 v197, v197
	v_rcp_f32_e32 v198, v198
	v_rcp_f32_e32 v199, v199
	v_rcp_f32_e32 v200, v200
	v_rcp_f32_e32 v201, v201
	v_rcp_f32_e32 v202, v202
	v_rcp_f32_e32 v203, v203
	v_pk_mul_f32 v[56:57], v[56:57], v[196:197]
	v_pk_mul_f32 v[58:59], v[58:59], v[198:199]
	v_pk_mul_f32 v[60:61], v[60:61], v[200:201]
	v_pk_mul_f32 v[62:63], v[62:63], v[202:203]
	s_nop 0
	s_nop 0
	s_nop 0
	s_nop 0

; __device__ __forceinline__ float gelu_tanh(float x) { const float u = 1.5957691216f * (x + 0.044715f * x * x * x); return x * __builtin_amdgcn_rcpf(1.f + __expf(-u)); }
; __device__ __forceinline__ void st_bf16x8(bf16_t* p, const f32x4 a, const f32x4 b) { uint4 o; o.x = cvt_pk_bf16(a[0], a[1]); o.y = cvt_pk_bf16(a[2], a[3]); o.z = cvt_pk_bf16(b[0], b[1]); o.w = cvt_pk_bf16(b[2], b[3]); *(uint4*)p = o; }
;     __device__ __forceinline__ void row(const f32x4 (&a)[2][2], int row, int pn, int wc, int fq) const {
;     ...
;             for (int bj = 0; bj < 2; ++bj) { f32x4 v0 = a[bj][0], v1 = a[bj][1];
;                 if (pn < 2) {
; #pragma unroll
;                     for (int j = 0; j < 4; ++j) { v0[j] = gelu_tanh(v0[j]); v1[j] = gelu_tanh(v1[j]); } }
;                 st_bf16x8(dst + bj * HALF, v0, v1); }
.LBB0_306:
	v_cvt_pk_bf16_f32 v52, v52, v53
	v_cvt_pk_bf16_f32 v53, v54, v55
	v_cvt_pk_bf16_f32 v54, v48, v49
	s_nop 0
	v_cvt_pk_bf16_f32 v55, v50, v51
	global_store_dwordx4 v[64:65], v[52:55], off offset:256
	v_add_u32_e32 v56, 0x90, v156
	s_and_b64 vcc, exec, s[8:9]
	s_mov_b64 s[0:1], -1
	s_cbranch_vccnz .LBB0_286
	s_branch .LBB0_307

; __device__ __forceinline__ float gelu_tanh(float x) { const float u = 1.5957691216f * (x + 0.044715f * x * x * x); return x * __builtin_amdgcn_rcpf(1.f + __expf(-u)); }
; __device__ __forceinline__ void st_bf16x8(bf16_t* p, const f32x4 a, const f32x4 b) { uint4 o; o.x = cvt_pk_bf16(a[0], a[1]); o.y = cvt_pk_bf16(a[2], a[3]); o.z = cvt_pk_bf16(b[0], b[1]); o.w = cvt_pk_bf16(b[2], b[3]); *(uint4*)p = o; }
;     __device__ __forceinline__ void row(const f32x4 (&a)[2][2], int row, int pn, int wc, int fq) const {
;     ...
;             for (int bj = 0; bj < 2; ++bj) { f32x4 v0 = a[bj][0], v1 = a[bj][1];
;                 if (pn < 2) {
; #pragma unroll
;                     for (int j = 0; j < 4; ++j) { v0[j] = gelu_tanh(v0[j]); v1[j] = gelu_tanh(v1[j]); } }
;                 st_bf16x8(dst + bj * HALF, v0, v1); }
.LBB0_322:
	v_cvt_pk_bf16_f32 v36, v36, v37
	v_cvt_pk_bf16_f32 v37, v38, v39
	v_cvt_pk_bf16_f32 v38, v32, v33
	s_nop 0
	v_cvt_pk_bf16_f32 v39, v34, v35
	global_store_dwordx4 v[48:49], v[36:39], off offset:256
	v_add_u32_e32 v40, 0xa0, v156
	s_and_b64 vcc, exec, s[8:9]
	s_mov_b64 s[0:1], -1
	s_cbranch_vccnz .LBB0_288
	s_branch .LBB0_323

; __device__ __forceinline__ float gelu_tanh(float x) { const float u = 1.5957691216f * (x + 0.044715f * x * x * x); return x * __builtin_amdgcn_rcpf(1.f + __expf(-u)); }
; __device__ __forceinline__ void st_bf16x8(bf16_t* p, const f32x4 a, const f32x4 b) { uint4 o; o.x = cvt_pk_bf16(a[0], a[1]); o.y = cvt_pk_bf16(a[2], a[3]); o.z = cvt_pk_bf16(b[0], b[1]); o.w = cvt_pk_bf16(b[2], b[3]); *(uint4*)p = o; }
;     __device__ __forceinline__ void row(const f32x4 (&a)[2][2], int row, int pn, int wc, int fq) const {
;     ...
;             for (int bj = 0; bj < 2; ++bj) { f32x4 v0 = a[bj][0], v1 = a[bj][1];
;                 if (pn < 2) {
; #pragma unroll
;                     for (int j = 0; j < 4; ++j) { v0[j] = gelu_tanh(v0[j]); v1[j] = gelu_tanh(v1[j]); } }
;                 st_bf16x8(dst + bj * HALF, v0, v1); }
.LBB0_338:
	v_cvt_pk_bf16_f32 v20, v20, v21
	v_cvt_pk_bf16_f32 v21, v22, v23
	v_cvt_pk_bf16_f32 v22, v16, v17
	s_nop 0
	v_cvt_pk_bf16_f32 v23, v18, v19
	global_store_dwordx4 v[32:33], v[20:23], off offset:256
	v_add_u32_e32 v24, 0xb0, v156
	s_and_b64 vcc, exec, s[8:9]
	s_mov_b64 s[0:1], -1
	s_cbranch_vccnz .LBB0_290
	s_branch .LBB0_339

; __device__ __forceinline__ float gelu_tanh(float x) { const float u = 1.5957691216f * (x + 0.044715f * x * x * x); return x * __builtin_amdgcn_rcpf(1.f + __expf(-u)); }
; __device__ __forceinline__ void st_bf16x8(bf16_t* p, const f32x4 a, const f32x4 b) { uint4 o; o.x = cvt_pk_bf16(a[0], a[1]); o.y = cvt_pk_bf16(a[2], a[3]); o.z = cvt_pk_bf16(b[0], b[1]); o.w = cvt_pk_bf16(b[2], b[3]); *(uint4*)p = o; }
;     __device__ __forceinline__ void row(const f32x4 (&a)[2][2], int row, int pn, int wc, int fq) const {
;     ...
;             for (int bj = 0; bj < 2; ++bj) { f32x4 v0 = a[bj][0], v1 = a[bj][1];
;                 if (pn < 2) {
; #pragma unroll
;                     for (int j = 0; j < 4; ++j) { v0[j] = gelu_tanh(v0[j]); v1[j] = gelu_tanh(v1[j]); } }
;                 st_bf16x8(dst + bj * HALF, v0, v1); }
;     ...
;         } else {
;             const int c = (pn - 6) * 128 + wc * 32 + 8 * fq;
;             const f32x4 z0 = a[0][0] * a[1][0], z1 = a[0][1] * a[1][1];
;             st_bf16x8(pZ + (size_t)row * 512 + c, z0, z1);
;             float* o = nullptr;
;             if (row < NP) { const int t = row & 2047; if (t >= 2046) o = out + O_CONVP + (size_t)((row >> 11) * 2 + (t - 2046)) * 512 + c; }
;             else if (row < NTOK) o = out + O_CONVS + (size_t)((row - NP) * 2 + 1) * 512 + c;
;             if (o) { *(f32x4*)o = z0; *(f32x4*)(o + 4) = z1; }
.LBB0_354:
	s_and_b64 s[0:1], s[80:81], exec
	v_ashrrev_i32_e32 v25, 31, v24
	s_cselect_b32 s1, s31, s49
	s_cselect_b32 s0, s30, s48
	v_lshlrev_b64 v[16:17], 10, v[24:25]
	v_lshl_add_u64 v[16:17], s[0:1], 0, v[16:17]
	s_lshl_b32 s64, s61, 1
	v_lshl_add_u64 v[16:17], v[16:17], 0, s[64:65]
	s_lshl_b32 s64, s91, 1
	v_lshl_add_u64 v[16:17], v[16:17], 0, s[64:65]
	v_lshlrev_b32_e32 v140, 1, v142
	v_lshl_add_u64 v[16:17], v[16:17], 0, v[140:141]
	s_and_b64 vcc, exec, s[4:5]
	v_cvt_pk_bf16_f32 v12, v12, v13
	v_cvt_pk_bf16_f32 v13, v14, v15
	v_cvt_pk_bf16_f32 v14, v8, v9
	v_cvt_pk_bf16_f32 v15, v10, v11
	global_store_dwordx4 v[16:17], v[12:15], off
	s_cbranch_vccnz .LBB0_207
	v_mov_b32_e32 v190, 0x3d372713
	v_mov_b32_e32 v192, 0xbfcc422a
	v_mov_b32_e32 v194, 0x3fb8aa3b
	v_pk_mul_f32 v[196:197], v[0:1], v[190:191] op_sel_hi:[1,0]
	v_pk_mul_f32 v[198:199], v[2:3], v[190:191] op_sel_hi:[1,0]
	v_pk_mul_f32 v[200:201], v[4:5], v[190:191] op_sel_hi:[1,0]
	v_pk_mul_f32 v[202:203], v[6:7], v[190:191] op_sel_hi:[1,0]
	v_pk_mul_f32 v[196:197], v[0:1], v[196:197]
	v_pk_mul_f32 v[198:199], v[2:3], v[198:199]
	v_pk_mul_f32 v[200:201], v[4:5], v[200:201]
	v_pk_mul_f32 v[202:203], v[6:7], v[202:203]
	v_pk_fma_f32 v[196:197], v[0:1], v[196:197], v[0:1]
	v_pk_fma_f32 v[198:199], v[2:3], v[198:199], v[2:3]
	v_pk_fma_f32 v[200:201], v[4:5], v[200:201], v[4:5]
	v_pk_fma_f32 v[202:203], v[6:7], v[202:203], v[6:7]
	v_pk_mul_f32 v[196:197], v[196:197], v[192:193] op_sel_hi:[1,0]
	v_pk_mul_f32 v[198:199], v[198:199], v[192:193] op_sel_hi:[1,0]
	v_pk_mul_f32 v[200:201], v[200:201], v[192:193] op_sel_hi:[1,0]
	v_pk_mul_f32 v[202:203], v[202:203], v[192:193] op_sel_hi:[1,0]
	v_pk_mul_f32 v[196:197], v[196:197], v[194:195] op_sel_hi:[1,0]
	v_pk_mul_f32 v[198:199], v[198:199], v[194:195] op_sel_hi:[1,0]
	v_pk_mul_f32 v[200:201], v[200:201], v[194:195] op_sel_hi:[1,0]
	v_pk_mul_f32 v[202:203], v[202:203], v[194:195] op_sel_hi:[1,0]
	v_exp_f32_e32 v196, v196
	v_exp_f32_e32 v197, v197
	v_exp_f32_e32 v198, v198
	v_exp_f32_e32 v199, v199
	v_exp_f32_e32 v200, v200
	v_exp_f32_e32 v201, v201
	v_exp_f32_e32 v202, v202
	v_exp_f32_e32 v203, v203
	v_pk_add_f32 v[196:197], v[196:197], 1.0 op_sel_hi:[1,0]
	v_pk_add_f32 v[198:199], v[198:199], 1.0 op_sel_hi:[1,0]
	v_pk_add_f32 v[200:201], v[200:201], 1.0 op_sel_hi:[1,0]
	v_pk_add_f32 v[202:203], v[202:203], 1.0 op_sel_hi:[1,0]
	v_rcp_f32_e32 v196, v196
	v_rcp_f32_e32 v197, v197
	v_rcp_f32_e32 v198, v198
	v_rcp_f32_e32 v199, v199
	v_rcp_f32_e32 v200, v200
	v_rcp_f32_e32 v201, v201
	v_rcp_f32_e32 v202, v202
	v_rcp_f32_e32 v203, v203
	v_pk_mul_f32 v[0:1], v[0:1], v[196:197]
	v_pk_mul_f32 v[2:3], v[2:3], v[198:199]
	v_pk_mul_f32 v[4:5], v[4:5], v[200:201]
	v_pk_mul_f32 v[6:7], v[6:7], v[202:203]
	s_branch .LBB0_207
.LBB0_236:
	s_and_b64 vcc, exec, s[6:7]
	s_cbranch_vccnz .LBB0_240
	v_ashrrev_i32_e32 v121, 31, v120
	v_lshlrev_b64 v[122:123], 10, v[120:121]
	s_cmpk_lt_u32 s73, 0x4080
	v_lshl_add_u64 v[122:123], s[50:51], 0, v[122:123]
	v_cmp_lt_i32_e32 vcc, s12, v120
	s_cselect_b64 s[0:1], -1, 0
	v_pk_mul_f32 v[114:115], v[110:111], v[102:103]
	v_pk_mul_f32 v[112:113], v[108:109], v[100:101]
	v_pk_mul_f32 v[118:119], v[106:107], v[98:99]
	v_pk_mul_f32 v[116:117], v[104:105], v[96:97]
	v_lshl_add_u64 v[126:127], v[154:155], 1, v[122:123]
	s_and_b64 s[82:83], vcc, s[0:1]
	v_cvt_pk_bf16_f32 v122, v112, v113
	v_cvt_pk_bf16_f32 v123, v114, v115
	v_cvt_pk_bf16_f32 v124, v116, v117
	v_cvt_pk_bf16_f32 v125, v118, v119
	global_store_dwordx4 v[126:127], v[122:125], off
	s_and_saveexec_b64 s[0:1], s[82:83]
	s_cbranch_execz .LBB0_239
	v_lshl_add_u32 v122, v120, 1, v189
	v_mov_b32_e32 v123, v141
	v_lshlrev_b64 v[122:123], 11, v[122:123]
	v_lshl_add_u64 v[122:123], s[66:67], 0, v[122:123]
	v_lshl_add_u64 v[122:123], v[154:155], 2, v[122:123]
	global_store_dwordx4 v[122:123], v[112:115], off
	global_store_dwordx4 v[122:123], v[116:119], off offset:16

.LBB0_245:
	s_cbranch_execnz .LBB0_232
	s_branch .LBB0_246
